# SB unit balance: odd-numbered units of a CU take the mirrored q block (idx xor 15, guarded on G%16==0) so every CU gets equal causal work
# speedup vs baseline: 1.0006x; 1.0002x over previous
.LBB0_393:
	s_nop 5
	ds_write2_b32 v125, v0, v16 offset1:32
	ds_write2_b32 v127, v1, v17 offset1:32
	ds_write2_b32 v141, v2, v18 offset1:32
	ds_write2_b32 v143, v3, v19 offset1:32
	ds_write2_b32 v145, v4, v20 offset1:32
	ds_write2_b32 v148, v5, v21 offset1:32
	ds_write2_b32 v149, v6, v22 offset1:32
	ds_write2_b32 v150, v7, v23 offset1:32
	ds_write2_b32 v151, v8, v24 offset1:32
	ds_write2_b32 v152, v9, v25 offset1:32
	ds_write2_b32 v153, v10, v26 offset1:32
	ds_write2_b32 v154, v11, v27 offset1:32
	ds_write2_b32 v155, v12, v28 offset1:32
	ds_write2_b32 v156, v13, v29 offset1:32
	ds_write2_b32 v157, v14, v30 offset1:32
	ds_write2_b32 v158, v15, v31 offset1:32
	s_waitcnt vmcnt(3)
	v_lshlrev_b32_e32 v10, 16, v92
	v_mul_f32_e32 v8, 0xbfb8aa3b, v10
	v_and_b32_e32 v11, 0xffff0000, v92
	v_exp_f32_e32 v8, v8
	v_mul_f32_e32 v9, 0xbfb8aa3b, v11
	v_exp_f32_e32 v12, v9
	ds_read_b128 v[0:3], v160
	ds_read_b128 v[4:7], v160 offset:16
	v_add_f32_e32 v8, 1.0, v8
	v_rcp_f32_e32 v13, v8
	v_add_f32_e32 v8, 1.0, v12
	v_rcp_f32_e32 v12, v8
	s_add_u32 s28, s38, s28
	v_mul_f32_e32 v10, v13, v10
	s_waitcnt lgkmcnt(1)
	v_mul_f32_e32 v0, v10, v0
	v_mul_f32_e32 v10, v12, v11
	v_lshlrev_b32_e32 v11, 16, v93
	v_mul_f32_e32 v12, 0xbfb8aa3b, v11
	v_and_b32_e32 v13, 0xffff0000, v93
	v_exp_f32_e32 v12, v12
	v_mul_f32_e32 v14, 0xbfb8aa3b, v13
	v_exp_f32_e32 v14, v14
	v_mul_f32_e32 v1, v10, v1
	v_add_f32_e32 v10, 1.0, v12
	v_rcp_f32_e32 v10, v10
	v_add_f32_e32 v12, 1.0, v14
	v_rcp_f32_e32 v12, v12
	v_cvt_pk_bf16_f32 v0, v0, v1
	v_mul_f32_e32 v1, v10, v11
	v_lshlrev_b32_e32 v10, 16, v94
	v_mul_f32_e32 v1, v1, v2
	v_mul_f32_e32 v2, v12, v13
	v_mul_f32_e32 v11, 0xbfb8aa3b, v10
	v_and_b32_e32 v12, 0xffff0000, v94
	v_exp_f32_e32 v11, v11
	v_mul_f32_e32 v13, 0xbfb8aa3b, v12
	v_exp_f32_e32 v13, v13
	v_mul_f32_e32 v2, v2, v3
	v_add_f32_e32 v3, 1.0, v11
	v_rcp_f32_e32 v3, v3
	v_add_f32_e32 v11, 1.0, v13
	v_rcp_f32_e32 v11, v11
	v_cvt_pk_bf16_f32 v1, v1, v2
	v_mul_f32_e32 v2, v3, v10
	s_waitcnt lgkmcnt(0)
	v_mul_f32_e32 v2, v2, v4
	v_mul_f32_e32 v3, v11, v12
	v_lshlrev_b32_e32 v4, 16, v95
	v_and_b32_e32 v11, 0xffff0000, v95
	v_mul_f32_e32 v10, 0xbfb8aa3b, v4
	v_mul_f32_e32 v12, 0xbfb8aa3b, v11
	v_exp_f32_e32 v10, v10
	v_exp_f32_e32 v12, v12
	v_mul_f32_e32 v3, v3, v5
	s_addc_u32 s29, s39, s29
	v_add_f32_e32 v5, 1.0, v10
	v_add_f32_e32 v10, 1.0, v12
	v_rcp_f32_e32 v5, v5
	v_rcp_f32_e32 v10, v10
	v_cvt_pk_bf16_f32 v2, v2, v3
	v_mov_b32_e32 v9, s29
	v_mul_f32_e32 v3, v5, v4
	v_mul_f32_e32 v4, v10, v11
	v_or_b32_e32 v8, s28, v126
	v_mul_f32_e32 v3, v3, v6
	v_mul_f32_e32 v4, v4, v7
	s_waitcnt vmcnt(2)
	v_lshlrev_b32_e32 v10, 16, v88
	v_cvt_pk_bf16_f32 v3, v3, v4
	v_lshlrev_b64 v[4:5], 7, v[8:9]
	v_mul_f32_e32 v8, 0xbfb8aa3b, v10
	v_and_b32_e32 v11, 0xffff0000, v88
	v_exp_f32_e32 v8, v8
	v_mul_f32_e32 v9, 0xbfb8aa3b, v11
	v_exp_f32_e32 v12, v9
	v_lshl_add_u64 v[4:5], v[128:129], 0, v[4:5]
	v_add_f32_e32 v8, 1.0, v8
	global_store_dwordx4 v[4:5], v[0:3], off
	v_rcp_f32_e32 v13, v8
	v_add_f32_e32 v8, 1.0, v12
	ds_read_b128 v[0:3], v160 offset:2176
	ds_read_b128 v[4:7], v160 offset:2192
	v_rcp_f32_e32 v12, v8
	v_mul_f32_e32 v10, v13, v10
	v_and_b32_e32 v13, 0xffff0000, v89
	s_waitcnt lgkmcnt(1)
	v_mul_f32_e32 v0, v10, v0
	v_mul_f32_e32 v10, v12, v11
	v_lshlrev_b32_e32 v11, 16, v89
	v_mul_f32_e32 v12, 0xbfb8aa3b, v11
	v_exp_f32_e32 v12, v12
	v_mul_f32_e32 v14, 0xbfb8aa3b, v13
	v_exp_f32_e32 v14, v14
	v_mul_f32_e32 v1, v10, v1
	v_add_f32_e32 v10, 1.0, v12
	v_rcp_f32_e32 v10, v10
	v_add_f32_e32 v12, 1.0, v14
	v_rcp_f32_e32 v12, v12
	v_cvt_pk_bf16_f32 v0, v0, v1
	v_mul_f32_e32 v1, v10, v11
	v_lshlrev_b32_e32 v10, 16, v90
	v_mul_f32_e32 v1, v1, v2
	v_mul_f32_e32 v2, v12, v13
	v_mul_f32_e32 v11, 0xbfb8aa3b, v10
	v_and_b32_e32 v12, 0xffff0000, v90
	v_exp_f32_e32 v11, v11
	v_mul_f32_e32 v13, 0xbfb8aa3b, v12
	v_exp_f32_e32 v13, v13
	v_mul_f32_e32 v2, v2, v3
	v_add_f32_e32 v3, 1.0, v11
	v_rcp_f32_e32 v3, v3
	v_add_f32_e32 v11, 1.0, v13
	v_rcp_f32_e32 v11, v11
	v_cvt_pk_bf16_f32 v1, v1, v2
	v_mul_f32_e32 v2, v3, v10
	s_waitcnt lgkmcnt(0)
	v_mul_f32_e32 v2, v2, v4
	v_mul_f32_e32 v3, v11, v12
	v_lshlrev_b32_e32 v4, 16, v91
	v_and_b32_e32 v11, 0xffff0000, v91
	v_mul_f32_e32 v10, 0xbfb8aa3b, v4
	v_mul_f32_e32 v12, 0xbfb8aa3b, v11
	v_exp_f32_e32 v10, v10
	v_exp_f32_e32 v12, v12
	v_mul_f32_e32 v3, v3, v5
	v_cvt_pk_bf16_f32 v2, v2, v3
	v_add_f32_e32 v5, 1.0, v10
	v_add_f32_e32 v10, 1.0, v12
	v_rcp_f32_e32 v5, v5
	v_rcp_f32_e32 v10, v10
	v_mov_b32_e32 v9, s29
	v_or_b32_e32 v8, s28, v140
	v_mul_f32_e32 v3, v5, v4
	v_mul_f32_e32 v4, v10, v11
	v_mul_f32_e32 v3, v3, v6
	v_mul_f32_e32 v4, v4, v7
	s_waitcnt vmcnt(2)
	v_lshlrev_b32_e32 v10, 16, v84
	v_cvt_pk_bf16_f32 v3, v3, v4
	v_lshlrev_b64 v[4:5], 7, v[8:9]
	v_mul_f32_e32 v8, 0xbfb8aa3b, v10
	v_and_b32_e32 v11, 0xffff0000, v84
	v_exp_f32_e32 v8, v8
	v_mul_f32_e32 v9, 0xbfb8aa3b, v11
	v_exp_f32_e32 v12, v9
	v_lshl_add_u64 v[4:5], v[128:129], 0, v[4:5]
	v_add_f32_e32 v8, 1.0, v8
	global_store_dwordx4 v[4:5], v[0:3], off
	v_rcp_f32_e32 v13, v8
	v_add_f32_e32 v8, 1.0, v12
	ds_read_b128 v[0:3], v160 offset:4352
	ds_read_b128 v[4:7], v160 offset:4368
	v_rcp_f32_e32 v12, v8
	v_mul_f32_e32 v10, v13, v10
	v_and_b32_e32 v13, 0xffff0000, v85
	s_waitcnt lgkmcnt(1)
	v_mul_f32_e32 v0, v10, v0
	v_mul_f32_e32 v10, v12, v11
	v_lshlrev_b32_e32 v11, 16, v85
	v_mul_f32_e32 v12, 0xbfb8aa3b, v11
	v_exp_f32_e32 v12, v12
	v_mul_f32_e32 v14, 0xbfb8aa3b, v13
	v_exp_f32_e32 v14, v14
	v_mul_f32_e32 v1, v10, v1
	v_add_f32_e32 v10, 1.0, v12
	v_rcp_f32_e32 v10, v10
	v_add_f32_e32 v12, 1.0, v14
	v_rcp_f32_e32 v12, v12
	v_cvt_pk_bf16_f32 v0, v0, v1
	v_mul_f32_e32 v1, v10, v11
	v_lshlrev_b32_e32 v10, 16, v86
	v_mul_f32_e32 v1, v1, v2
	v_mul_f32_e32 v2, v12, v13
	v_mul_f32_e32 v11, 0xbfb8aa3b, v10
	v_and_b32_e32 v12, 0xffff0000, v86
	v_exp_f32_e32 v11, v11
	v_mul_f32_e32 v13, 0xbfb8aa3b, v12
	v_exp_f32_e32 v13, v13
	v_mul_f32_e32 v2, v2, v3
	v_add_f32_e32 v3, 1.0, v11
	v_rcp_f32_e32 v3, v3
	v_add_f32_e32 v11, 1.0, v13
	v_rcp_f32_e32 v11, v11
	v_cvt_pk_bf16_f32 v1, v1, v2
	v_mul_f32_e32 v2, v3, v10
	s_waitcnt lgkmcnt(0)
	v_mul_f32_e32 v2, v2, v4
	v_mul_f32_e32 v3, v11, v12
	v_lshlrev_b32_e32 v4, 16, v87
	v_and_b32_e32 v11, 0xffff0000, v87
	v_mul_f32_e32 v10, 0xbfb8aa3b, v4
	v_mul_f32_e32 v12, 0xbfb8aa3b, v11
	v_exp_f32_e32 v10, v10
	v_exp_f32_e32 v12, v12
	v_mul_f32_e32 v3, v3, v5
	v_cvt_pk_bf16_f32 v2, v2, v3
	v_add_f32_e32 v5, 1.0, v10
	v_add_f32_e32 v10, 1.0, v12
	v_rcp_f32_e32 v5, v5
	v_rcp_f32_e32 v10, v10
	v_mov_b32_e32 v9, s29
	v_or_b32_e32 v8, s28, v142
	v_mul_f32_e32 v3, v5, v4
	v_mul_f32_e32 v4, v10, v11
	v_mul_f32_e32 v3, v3, v6
	v_mul_f32_e32 v4, v4, v7
	s_waitcnt vmcnt(2)
	v_lshlrev_b32_e32 v10, 16, v80
	v_cvt_pk_bf16_f32 v3, v3, v4
	v_lshlrev_b64 v[4:5], 7, v[8:9]
	v_mul_f32_e32 v8, 0xbfb8aa3b, v10
	v_and_b32_e32 v11, 0xffff0000, v80
	v_exp_f32_e32 v8, v8
	v_mul_f32_e32 v9, 0xbfb8aa3b, v11
	v_exp_f32_e32 v12, v9
	v_lshl_add_u64 v[4:5], v[128:129], 0, v[4:5]
	v_add_f32_e32 v8, 1.0, v8
	global_store_dwordx4 v[4:5], v[0:3], off
	v_rcp_f32_e32 v13, v8
	v_add_f32_e32 v8, 1.0, v12
	ds_read_b128 v[0:3], v160 offset:6528
	ds_read_b128 v[4:7], v160 offset:6544
	v_rcp_f32_e32 v12, v8
	v_mul_f32_e32 v10, v13, v10
	v_and_b32_e32 v13, 0xffff0000, v81
	s_waitcnt lgkmcnt(1)
	v_mul_f32_e32 v0, v10, v0
	v_mul_f32_e32 v10, v12, v11
	v_lshlrev_b32_e32 v11, 16, v81
	v_mul_f32_e32 v12, 0xbfb8aa3b, v11
	v_exp_f32_e32 v12, v12
	v_mul_f32_e32 v14, 0xbfb8aa3b, v13
	v_exp_f32_e32 v14, v14
	v_mul_f32_e32 v1, v10, v1
	v_add_f32_e32 v10, 1.0, v12
	v_rcp_f32_e32 v10, v10
	v_add_f32_e32 v12, 1.0, v14
	v_rcp_f32_e32 v12, v12
	v_cvt_pk_bf16_f32 v0, v0, v1
	v_mul_f32_e32 v1, v10, v11
	v_lshlrev_b32_e32 v10, 16, v82
	v_mul_f32_e32 v1, v1, v2
	v_mul_f32_e32 v2, v12, v13
	v_mul_f32_e32 v11, 0xbfb8aa3b, v10
	v_and_b32_e32 v12, 0xffff0000, v82
	v_exp_f32_e32 v11, v11
	v_mul_f32_e32 v13, 0xbfb8aa3b, v12
	v_exp_f32_e32 v13, v13
	v_mul_f32_e32 v2, v2, v3
	v_add_f32_e32 v3, 1.0, v11
	v_rcp_f32_e32 v3, v3
	v_add_f32_e32 v11, 1.0, v13
	v_rcp_f32_e32 v11, v11
	v_cvt_pk_bf16_f32 v1, v1, v2
	v_mul_f32_e32 v2, v3, v10
	s_waitcnt lgkmcnt(0)
	v_mul_f32_e32 v2, v2, v4
	v_mul_f32_e32 v3, v11, v12
	v_lshlrev_b32_e32 v4, 16, v83
	v_and_b32_e32 v11, 0xffff0000, v83
	v_mul_f32_e32 v10, 0xbfb8aa3b, v4
	v_mul_f32_e32 v12, 0xbfb8aa3b, v11
	v_exp_f32_e32 v10, v10
	v_exp_f32_e32 v12, v12
	v_mul_f32_e32 v3, v3, v5
	v_cvt_pk_bf16_f32 v2, v2, v3
	v_add_f32_e32 v5, 1.0, v10
	v_add_f32_e32 v10, 1.0, v12
	v_rcp_f32_e32 v5, v5
	v_rcp_f32_e32 v10, v10
	v_mov_b32_e32 v9, s29
	v_or_b32_e32 v8, s28, v144
	v_mul_f32_e32 v3, v5, v4
	v_mul_f32_e32 v4, v10, v11
	v_mul_f32_e32 v3, v3, v6
	v_mul_f32_e32 v4, v4, v7
	v_cvt_pk_bf16_f32 v3, v3, v4
	v_lshlrev_b64 v[4:5], 7, v[8:9]
	v_lshl_add_u64 v[4:5], v[128:129], 0, v[4:5]
	global_store_dwordx4 v[4:5], v[0:3], off
	v_readlane_b32 s28, v254, 0
	v_mov_b64_e32 v[16:17], v[96:97]
	v_mov_b64_e32 v[0:1], v[32:33]
	v_mov_b64_e32 v[20:21], v[100:101]
	v_mov_b64_e32 v[24:25], v[104:105]
	s_add_i32 s26, s26, s28
	s_and_b32 vcc_lo, s28, 0x78
	s_cselect_b32 vcc_lo, 0, 0x78
	s_xor_b32 s26, s26, vcc_lo
	s_andn2_b64 vcc, exec, s[34:35]
	v_mov_b64_e32 v[2:3], v[34:35]
	v_mov_b64_e32 v[18:19], v[98:99]
	v_mov_b64_e32 v[22:23], v[102:103]
	v_mov_b64_e32 v[26:27], v[106:107]
	v_readlane_b32 s29, v254, 1
	s_cbranch_vccz .LBB0_407

.LBB0_405:
	s_add_i32 s27, s27, s76
	s_and_b32 s34, s76, 15
	s_cselect_b32 s34, 0, 15
	s_xor_b32 s27, s27, s34
	s_cmpk_gt_i32 s27, 0x3ff
	s_cselect_b64 s[34:35], -1, 0
	s_and_b64 vcc, exec, s[34:35]
	s_cbranch_vccnz .LBB0_393
	s_ashr_i32 s86, s27, 8
	s_lshl_b32 s4, s27, 3
	s_and_b32 s4, s4, 0x78
	s_lshl_b32 s80, s27, 10
	s_ashr_i32 s87, s86, 31
	s_add_i32 s4, s4, s3
	s_and_b32 s80, s80, 0x3c000
	s_lshl_b64 s[86:87], s[86:87], 12
	s_add_u32 s80, s86, s80
	s_addc_u32 s83, s87, 0
	s_lshl_b32 s4, s4, 5
	s_ashr_i32 s86, s4, 31
	s_add_u32 s4, s80, s4
	s_addc_u32 s80, s83, s86
	s_waitcnt vmcnt(7)
	v_mov_b32_e32 v33, s80
	v_or_b32_e32 v32, s4, v124
	v_lshlrev_b64 v[32:33], 7, v[32:33]
	v_lshl_add_u64 v[36:37], v[130:131], 0, v[32:33]
	v_lshl_add_u64 v[138:139], v[132:133], 0, v[32:33]
	v_mov_b32_e32 v33, s80
	v_or_b32_e32 v32, s4, v126
	v_lshlrev_b64 v[32:33], 7, v[32:33]
	v_lshl_add_u64 v[136:137], v[134:135], 0, v[32:33]
	global_load_dwordx4 v[48:51], v[36:37], off
	global_load_dwordx4 v[52:55], v[36:37], off offset:32
	global_load_dwordx4 v[32:35], v[138:139], off
	global_load_dwordx4 v[96:99], v[138:139], off offset:32
	global_load_dwordx4 v[64:67], v[136:137], off
	global_load_dwordx4 v[68:71], v[136:137], off offset:1024
	global_load_dwordx4 v[56:59], v[36:37], off offset:64
	global_load_dwordx4 v[60:63], v[36:37], off offset:96
	global_load_dwordx4 v[100:103], v[138:139], off offset:64
	global_load_dwordx4 v[104:107], v[138:139], off offset:96
	global_load_dwordx4 v[72:75], v[136:137], off offset:2048
	global_load_dwordx4 v[76:79], v[136:137], off offset:3072
	s_branch .LBB0_393
